# v54 + P4 softmax: ALiBi lane part moved from the 80 scores to the sink logit (softmax shift invariance; exchanged max converted between the two lane frames), each score bias one v_fmamk instead of two
# baseline (speedup 1.0000x reference)
; #define LAS __attribute__((address_space(3)))
; __device__ __forceinline__ void attn_pool_phase(LAS unsigned char* lds, bf16* QKV, bf16* PL, const float* sinks, int G, int bid) {
;     ...
;         const float slopeL = __builtin_bit_cast(float, __builtin_amdgcn_readfirstlane(__builtin_bit_cast(int, __builtin_amdgcn_exp2f(-0.5f * (float)(h + 1)) * LOG2E))), sink2 = sinks[h] * LOG2E;
;         LAS unsigned char* ost = lds + LDS_OST + wid * (32 * OROWB);
;         for (int i = 0; i < 4; ++i) {
;             bf16* orow = QKV + (rowbase + n * 128 + 32 * i) * NIN + h * 64;
;             bf16x8 qf[4];
; #pragma unroll
;             for (int d0 = 0; d0 < 4; ++d0) qf[d0] = qn[d0];
;             if (i < 3) {
; #pragma unroll
;                 for (int d0 = 0; d0 < 4; ++d0) qn[d0] = *(const bf16x8*)(qbase + (size_t)(32 * (i + 1)) * NIN + d0 * 16); }
;             f32x16 S[5];
; #pragma unroll
;             for (int j = 0; j < 5; ++j) { const LAS unsigned char* kp = lds + (32 * (i + j) + q) * KROWB + hi * 16;
;                 f32x16 a = {};
; #pragma unroll
;                 for (int d0 = 0; d0 < 4; ++d0) a = __builtin_amdgcn_mfma_f32_32x32x16_bf16(*(const LAS bf16x8*)(kp + d0 * 32), qf[d0], a, 0, 0, 0);
;                 S[j] = a; }
;             float mx = sink2;
;             int qo = q - 4 * hi; asm volatile("" : "+v"(qo));
;             const float lb = -slopeL * (float)(128 + qo);
; #pragma unroll
;             for (int j = 0; j < 5; ++j) { const bool tile_ok = !(n == 0 && i + j < 4); const float lbj = lb + slopeL * (32.0f * (float)j);
; #pragma unroll
;                 for (int r = 0; r < 16; ++r) { const int crc = (r & 3) + 8 * (r >> 2);
;                     float s = S[j][r] + (lbj + slopeL * (float)crc);
;                     if (j == 0) s = (crc > qo) ? s : -INFINITY;
;                     if (j == 4) s = (crc <= qo) ? s : -INFINITY;
;                     if (!tile_ok) s = -INFINITY;
;                     S[j][r] = s; mx = fmaxf(mx, s); } }
.LBB0_502:
	s_lshl_b32 s8, s7, 2
	v_mov_b32_e32 v0, s8
	global_load_dword v4, v0, s[64:65]
	s_lshr_b32 s2, s44, 1
	s_lshl_b32 s8, s19, 6
	s_and_b32 s2, s2, 63
	s_add_i32 s9, s7, 1
	s_and_b32 s8, s8, 0x200
	s_mul_i32 s45, s2, 0xf0000
	s_lshl_b32 s46, s2, 7
	v_cvt_f32_u32_e32 v2, s9
	s_add_i32 s2, s18, s8
	s_lshl_b64 s[8:9], s[2:3], 1
	s_mul_i32 s44, s6, 0x3c00000
	s_cmp_lg_u32 s42, 0
	s_mul_hi_i32 s37, s6, 0x3c00000
	s_cselect_b64 s[10:11], -1, 0
	s_add_u32 s2, s44, s45
	v_mul_f32_e32 v2, -0.5, v2
	s_addc_u32 s37, s37, 0
	v_mov_b64_e32 v[0:1], s[8:9]
	v_exp_f32_e32 v2, v2
	s_add_u32 s8, s2, s8
	s_addc_u32 s9, s37, s9
	v_lshl_add_u64 v[166:167], v[162:163], 0, s[8:9]
	s_add_u32 s8, s46, s34
	s_addc_u32 s9, 0, s35
	v_readfirstlane_b32 s2, v2
	v_lshl_add_u64 v[2:3], s[8:9], 0, v[86:87]
	v_mad_u64_u32 v[0:1], s[8:9], v2, s15, v[0:1]
	s_waitcnt vmcnt(1)
	v_mov_b64_e32 v[116:117], v[132:133]
	v_mov_b64_e32 v[120:121], v[136:137]
	v_mov_b64_e32 v[124:125], v[140:141]
	v_mul_f32_e32 v161, s2, v187
	v_mad_i32_i24 v1, v3, s15, v1
	v_mov_b64_e32 v[130:131], v[34:35]
	s_mov_b32 s36, 0
	s_mov_b64 s[6:7], 0
	v_mov_b32_e32 v210, v179
	v_mov_b32_e32 v211, v178
	v_mov_b64_e32 v[118:119], v[134:135]
	v_mov_b64_e32 v[122:123], v[138:139]
	v_mov_b64_e32 v[126:127], v[142:143]
	v_mul_f32_e32 v190, 0, v161
	v_mbcnt_lo_u32_b32 v250, -1, 0
	v_mbcnt_hi_u32_b32 v250, -1, v250
	v_lshrrev_b32_e32 v250, 5, v250
	v_cvt_f32_u32_e32 v250, v250
	v_fma_f32 v250, v250, -2.0, 1.0
	v_mul_f32_e32 v250, 4.0, v250
	v_mul_f32_e32 v250, v161, v250
	v_add_f32_e32 v191, v161, v161
	v_mul_f32_e32 v192, 0x40400000, v161
	v_mul_f32_e32 v193, 0x41000000, v161
	v_mul_f32_e32 v194, 0x41100000, v161
	v_mul_f32_e32 v195, 0x41200000, v161
	v_mul_f32_e32 v196, 0x41300000, v161
	v_mul_f32_e32 v197, 0x41800000, v161
	v_mul_f32_e32 v198, 0x41880000, v161
	v_mul_f32_e32 v199, 0x41900000, v161
	v_mul_f32_e32 v200, 0x41980000, v161
	v_mul_f32_e32 v201, 0x41c00000, v161
	v_mul_f32_e32 v202, 0x41c80000, v161
	v_mul_f32_e32 v203, 0x41d00000, v161
	v_mul_f32_e32 v204, 0x41d80000, v161
	v_mul_f32_e32 v205, 0x42000000, v161
	v_mul_f32_e32 v206, 0x42800000, v161
	v_mul_f32_e32 v207, 0x42c00000, v161
	v_mul_f32_e32 v208, 0x43000000, v161
	v_lshl_add_u64 v[168:169], v[164:165], 0, v[0:1]
	v_mov_b64_e32 v[128:129], v[32:33]
	s_waitcnt vmcnt(0)
	v_mul_f32_e32 v209, 0x3fb8aa3b, v4
	s_branch .LBB0_504
.LBB0_503:
	ds_read_b128 v[0:3], v210
	ds_read_b128 v[16:19], v210 offset:32
	v_mov_b32_e32 v222, v174
	s_add_i32 s2, s36, 1
	s_waitcnt lgkmcnt(1)
	v_mfma_f32_32x32x16_bf16 v[0:15], v[0:3], v[32:35], 0
	s_waitcnt lgkmcnt(0)
	v_mfma_f32_32x32x16_bf16 v[0:15], v[16:19], v[140:143], v[0:15]
	ds_read_b128 v[16:19], v210 offset:64
	ds_read_b128 v[20:23], v210 offset:96
	s_waitcnt lgkmcnt(1)
	v_mfma_f32_32x32x16_bf16 v[0:15], v[16:19], v[136:139], v[0:15]
	ds_read_b128 v[16:19], v210 offset:18432
	ds_read_b128 v[64:67], v210 offset:4608
	ds_read_b128 v[60:63], v210 offset:4640
	ds_read_b128 v[36:39], v210 offset:18464
	ds_read_b128 v[56:59], v210 offset:4672
	ds_read_b128 v[52:55], v210 offset:4704
	ds_read_b128 v[48:51], v210 offset:9216
	ds_read_b128 v[156:159], v210 offset:9248
	ds_read_b128 v[44:47], v210 offset:9280
	ds_read_b128 v[40:43], v210 offset:9312
	ds_read_b128 v[72:75], v210 offset:18496
	s_waitcnt lgkmcnt(11)
	v_mfma_f32_32x32x16_bf16 v[0:15], v[20:23], v[132:135], v[0:15]
	s_waitcnt lgkmcnt(10)
	v_mfma_f32_32x32x16_bf16 v[16:31], v[16:19], v[32:35], 0
	s_waitcnt lgkmcnt(7)
	v_mfma_f32_32x32x16_bf16 v[16:31], v[36:39], v[140:143], v[16:31]
	ds_read_b128 v[36:39], v210 offset:13824
	ds_read_b128 v[152:155], v210 offset:13856
	ds_read_b128 v[148:151], v210 offset:13888
	ds_read_b128 v[144:147], v210 offset:13920
	ds_read_b128 v[68:71], v210 offset:18528
	v_add_u32_e32 v210, 0x1200, v210
	v_add_u32_e32 v76, 0x80, v222
	v_cvt_f32_i32_e32 v221, v76
	v_cmp_gt_i32_e32 vcc, 0, v222
	v_fma_f32 v223, -v161, v221, v190
	v_sub_f32_e32 v249, v209, v223
	s_waitcnt lgkmcnt(5)
	v_mfma_f32_32x32x16_bf16 v[16:31], v[72:75], v[136:139], v[16:31]
	v_fmamk_f32 v0, v161, 0x00000000, v0
	s_waitcnt lgkmcnt(0)
	v_mfma_f32_32x32x16_bf16 v[16:31], v[68:71], v[132:135], v[16:31]
	s_nop 11
	v_fmamk_f32 v16, v161, 0x43000000, v16
	v_mfma_f32_32x32x16_bf16 v[64:79], v[64:67], v[32:35], 0
	v_cndmask_b32_e32 v219, v16, v189, vcc
	s_and_b64 vcc, s[10:11], vcc
	v_fmamk_f32 v1, v161, 0x3f800000, v1
	v_cndmask_b32_e32 v0, v189, v0, vcc
	v_fmamk_f32 v16, v161, 0x43010000, v17
	v_mfma_f32_32x32x16_bf16 v[64:79], v[60:63], v[140:143], v[64:79]
	v_cmp_gt_i32_e32 vcc, 1, v222
	v_fmamk_f32 v2, v161, 0x40000000, v2
	v_cndmask_b32_e32 v220, v16, v189, vcc
	s_and_b64 vcc, s[10:11], vcc
	v_cndmask_b32_e32 v1, v189, v1, vcc
	v_mfma_f32_32x32x16_bf16 v[64:79], v[56:59], v[136:139], v[64:79]
	v_fmamk_f32 v17, v161, 0x43020000, v18
	v_cmp_gt_i32_e32 vcc, 2, v222
	v_max3_f32 v16, v249, v0, v1
	s_nop 0
	v_cndmask_b32_e32 v217, v17, v189, vcc
	s_and_b64 vcc, s[10:11], vcc
	v_mfma_f32_32x32x16_bf16 v[64:79], v[52:55], v[132:135], v[64:79]
	v_fmamk_f32 v3, v161, 0x40400000, v3
	v_cndmask_b32_e32 v2, v189, v2, vcc
	v_fmamk_f32 v17, v161, 0x43030000, v19
	v_cmp_gt_i32_e32 vcc, 3, v222
	v_mfma_f32_32x32x16_bf16 v[48:63], v[48:51], v[32:35], 0
	s_nop 0
	v_cndmask_b32_e32 v216, v17, v189, vcc
	s_and_b64 vcc, s[10:11], vcc
	v_fmamk_f32 v4, v161, 0x41000000, v4
	v_cndmask_b32_e32 v3, v189, v3, vcc
	v_fmamk_f32 v17, v161, 0x43080000, v20
	v_mfma_f32_32x32x16_bf16 v[48:63], v[156:159], v[140:143], v[48:63]
	v_cmp_gt_i32_e32 vcc, 8, v222
	v_max3_f32 v16, v16, v2, v3
	s_nop 0
	v_cndmask_b32_e32 v214, v17, v189, vcc
	s_and_b64 vcc, s[10:11], vcc
	v_fmamk_f32 v5, v161, 0x41100000, v5
; __device__ __forceinline__ void attn_pool_phase(LAS unsigned char* lds, bf16* QKV, bf16* PL, const float* sinks, int G, int bid) {
;     ...
;             float mx = sink2;
;             int qo = q - 4 * hi; asm volatile("" : "+v"(qo));
;             const float lb = -slopeL * (float)(128 + qo);
; #pragma unroll
;             for (int j = 0; j < 5; ++j) { const bool tile_ok = !(n == 0 && i + j < 4); const float lbj = lb + slopeL * (32.0f * (float)j);
; #pragma unroll
;                 for (int r = 0; r < 16; ++r) { const int crc = (r & 3) + 8 * (r >> 2);
;                     float s = S[j][r] + (lbj + slopeL * (float)crc);
;                     if (j == 0) s = (crc > qo) ? s : -INFINITY;
;                     if (j == 4) s = (crc <= qo) ? s : -INFINITY;
;                     if (!tile_ok) s = -INFINITY;
;                     S[j][r] = s; mx = fmaxf(mx, s); } }
	v_mfma_f32_32x32x16_bf16 v[48:63], v[44:47], v[136:139], v[48:63]
	v_cndmask_b32_e32 v4, v189, v4, vcc
	v_fmamk_f32 v17, v161, 0x43090000, v21
	v_cmp_gt_i32_e32 vcc, 9, v222
	s_nop 1
	v_cndmask_b32_e32 v213, v17, v189, vcc
	v_mfma_f32_32x32x16_bf16 v[48:63], v[40:43], v[132:135], v[48:63]
	s_and_b64 vcc, s[10:11], vcc
	v_fmamk_f32 v6, v161, 0x41200000, v6
	v_cndmask_b32_e32 v5, v189, v5, vcc
	v_fmamk_f32 v17, v161, 0x430a0000, v22
	v_cmp_gt_i32_e32 vcc, 10, v222
	v_max3_f32 v16, v16, v4, v5
	v_mfma_f32_32x32x16_bf16 v[32:47], v[36:39], v[32:35], 0
	v_cndmask_b32_e32 v215, v17, v189, vcc
	s_and_b64 vcc, s[10:11], vcc
	v_fmamk_f32 v7, v161, 0x41300000, v7
	v_cndmask_b32_e32 v6, v189, v6, vcc
	v_fmamk_f32 v17, v161, 0x430b0000, v23
	v_cmp_gt_i32_e32 vcc, 11, v222
	v_mfma_f32_32x32x16_bf16 v[32:47], v[152:155], v[140:143], v[32:47]
	s_nop 0
	v_cndmask_b32_e32 v212, v17, v189, vcc
	s_and_b64 vcc, s[10:11], vcc
	v_fmamk_f32 v8, v161, 0x41800000, v8
	v_cndmask_b32_e32 v7, v189, v7, vcc
	v_fmamk_f32 v17, v161, 0x43100000, v24
	v_cmp_gt_i32_e32 vcc, 16, v222
	v_mfma_f32_32x32x16_bf16 v[32:47], v[148:151], v[136:139], v[32:47]
	v_max3_f32 v16, v16, v6, v7
	v_cndmask_b32_e32 v156, v17, v189, vcc
	s_and_b64 vcc, s[10:11], vcc
	v_fmamk_f32 v9, v161, 0x41880000, v9
	v_cndmask_b32_e32 v8, v189, v8, vcc
	v_fmamk_f32 v17, v161, 0x43110000, v25
	v_cmp_gt_i32_e32 vcc, 17, v222
	v_mfma_f32_32x32x16_bf16 v[32:47], v[144:147], v[132:135], v[32:47]
	s_nop 0
	v_cndmask_b32_e32 v158, v17, v189, vcc
	s_and_b64 vcc, s[10:11], vcc
	v_fmamk_f32 v10, v161, 0x41900000, v10
	v_cndmask_b32_e32 v9, v189, v9, vcc
	v_fmamk_f32 v17, v161, 0x43120000, v26
	v_cmp_gt_i32_e32 vcc, 18, v222
	v_max3_f32 v16, v16, v8, v9
	s_nop 0
	v_cndmask_b32_e32 v157, v17, v189, vcc
	s_and_b64 vcc, s[10:11], vcc
	v_fmamk_f32 v11, v161, 0x41980000, v11
	v_cndmask_b32_e32 v10, v189, v10, vcc
	v_fmamk_f32 v17, v161, 0x43130000, v27
	v_cmp_gt_i32_e32 vcc, 19, v222
	s_nop 1
	v_cndmask_b32_e32 v140, v17, v189, vcc
	s_and_b64 vcc, s[10:11], vcc
	v_fmamk_f32 v12, v161, 0x41c00000, v12
	v_cndmask_b32_e32 v11, v189, v11, vcc
	v_fmamk_f32 v17, v161, 0x43180000, v28
	v_cmp_gt_i32_e32 vcc, 24, v222
	v_max3_f32 v16, v16, v10, v11
	s_nop 0
	v_cndmask_b32_e32 v136, v17, v189, vcc
	s_and_b64 vcc, s[10:11], vcc
	v_fmamk_f32 v13, v161, 0x41c80000, v13
	v_cndmask_b32_e32 v12, v189, v12, vcc
	v_fmamk_f32 v17, v161, 0x43190000, v29
	v_cmp_gt_i32_e32 vcc, 25, v222
	s_nop 1
	v_cndmask_b32_e32 v133, v17, v189, vcc
	s_and_b64 vcc, s[10:11], vcc
	v_fmamk_f32 v14, v161, 0x41d00000, v14
	v_cndmask_b32_e32 v13, v189, v13, vcc
	v_fmamk_f32 v17, v161, 0x431a0000, v30
	v_cmp_gt_i32_e32 vcc, 26, v222
	v_max3_f32 v16, v16, v12, v13
	s_nop 0
	v_cndmask_b32_e32 v134, v17, v189, vcc
	s_and_b64 vcc, s[10:11], vcc
	v_fmamk_f32 v15, v161, 0x41d80000, v15
	v_cndmask_b32_e32 v14, v189, v14, vcc
	v_fmamk_f32 v17, v161, 0x431b0000, v31
	v_cmp_gt_i32_e32 vcc, 27, v222
	s_nop 1
	v_cndmask_b32_e32 v132, v17, v189, vcc
	v_fmamk_f32 v19, v161, 0x42040000, v65
	v_fmamk_f32 v20, v161, 0x42080000, v66
	v_fmamk_f32 v48, v161, 0x42800000, v48
	v_fmamk_f32 v49, v161, 0x42820000, v49
	v_fmamk_f32 v50, v161, 0x42840000, v50
	v_fmamk_f32 v51, v161, 0x42860000, v51
	v_fmamk_f32 v52, v161, 0x42900000, v52
	v_fmamk_f32 v53, v161, 0x42920000, v53
	v_fmamk_f32 v54, v161, 0x42940000, v54
	v_fmamk_f32 v55, v161, 0x42960000, v55
	s_and_b64 vcc, s[10:11], vcc
	v_fmamk_f32 v56, v161, 0x42a00000, v56
	s_cmp_gt_u32 s36, 2
	v_fmamk_f32 v57, v161, 0x42a20000, v57
	s_cselect_b64 s[8:9], -1, 0
	v_fmamk_f32 v58, v161, 0x42a40000, v58
	v_cndmask_b32_e32 v15, v189, v15, vcc
	s_or_b64 vcc, s[10:11], s[8:9]
	v_fmamk_f32 v59, v161, 0x42a60000, v59
	v_fmamk_f32 v18, v161, 0x42000000, v64
	s_cmp_gt_u32 s36, 1
	v_fmamk_f32 v60, v161, 0x42b00000, v60
	v_fmamk_f32 v21, v161, 0x420c0000, v67
	v_fmamk_f32 v22, v161, 0x42200000, v68
	v_fmamk_f32 v23, v161, 0x42240000, v69
	v_fmamk_f32 v24, v161, 0x42280000, v70
	v_fmamk_f32 v25, v161, 0x422c0000, v71
	v_fmamk_f32 v26, v161, 0x42400000, v72
	v_fmamk_f32 v27, v161, 0x42440000, v73
	v_fmamk_f32 v28, v161, 0x42480000, v74
	v_fmamk_f32 v29, v161, 0x424c0000, v75
	v_fmamk_f32 v30, v161, 0x42600000, v76
	v_fmamk_f32 v31, v161, 0x42640000, v77
	v_fmamk_f32 v64, v161, 0x42680000, v78
	v_fmamk_f32 v17, v161, 0x426c0000, v79
	s_cselect_b64 s[8:9], -1, 0
	v_fmamk_f32 v61, v161, 0x42b20000, v61
	v_cndmask_b32_e32 v18, v189, v18, vcc
	v_cndmask_b32_e32 v19, v189, v19, vcc
	v_cndmask_b32_e32 v20, v189, v20, vcc
	v_cndmask_b32_e32 v21, v189, v21, vcc
	v_cndmask_b32_e32 v22, v189, v22, vcc
	v_cndmask_b32_e32 v23, v189, v23, vcc
	v_cndmask_b32_e32 v24, v189, v24, vcc
	v_cndmask_b32_e32 v25, v189, v25, vcc
	v_cndmask_b32_e32 v26, v189, v26, vcc
	v_cndmask_b32_e32 v27, v189, v27, vcc
	v_cndmask_b32_e32 v28, v189, v28, vcc
	v_cndmask_b32_e32 v29, v189, v29, vcc
	v_cndmask_b32_e32 v30, v189, v30, vcc
	v_cndmask_b32_e32 v31, v189, v31, vcc
	v_cndmask_b32_e32 v64, v189, v64, vcc
	v_cndmask_b32_e32 v17, v189, v17, vcc
	s_or_b64 vcc, s[10:11], s[8:9]
	v_fmamk_f32 v63, v161, 0x42b60000, v63
	s_or_b32 s8, s36, s42
	v_fmamk_f32 v62, v161, 0x42b40000, v62
	s_cmp_eq_u32 s8, 0
	v_cndmask_b32_e32 v48, v189, v48, vcc
	v_cndmask_b32_e32 v49, v189, v49, vcc
	v_cndmask_b32_e32 v50, v189, v50, vcc
	v_cndmask_b32_e32 v51, v189, v51, vcc
	v_cndmask_b32_e32 v52, v189, v52, vcc
	v_cndmask_b32_e32 v53, v189, v53, vcc
	v_cndmask_b32_e32 v54, v189, v54, vcc
	v_cndmask_b32_e32 v55, v189, v55, vcc
	v_cndmask_b32_e32 v56, v189, v56, vcc
	v_cndmask_b32_e32 v57, v189, v57, vcc
	v_cndmask_b32_e32 v58, v189, v58, vcc
	v_cndmask_b32_e32 v59, v189, v59, vcc
	v_cndmask_b32_e32 v60, v189, v60, vcc
; __device__ __forceinline__ void attn_pool_phase(LAS unsigned char* lds, bf16* QKV, bf16* PL, const float* sinks, int G, int bid) {
;     ...
;             for (int j = 0; j < 5; ++j) { const bool tile_ok = !(n == 0 && i + j < 4); const float lbj = lb + slopeL * (32.0f * (float)j);
; #pragma unroll
;                 for (int r = 0; r < 16; ++r) { const int crc = (r & 3) + 8 * (r >> 2);
;                     float s = S[j][r] + (lbj + slopeL * (float)crc);
;                     if (j == 0) s = (crc > qo) ? s : -INFINITY;
;                     if (j == 4) s = (crc <= qo) ? s : -INFINITY;
;                     if (!tile_ok) s = -INFINITY;
;                     S[j][r] = s; mx = fmaxf(mx, s); } }
;             mx = fmaxf(mx, __shfl_xor(mx, 32));
;             float l = 0.f;
; #pragma unroll
;             for (int j = 0; j < 5; ++j)
; #pragma unroll
;                 for (int r = 0; r < 16; ++r) { const float p = __builtin_amdgcn_exp2f(S[j][r] - mx); S[j][r] = p; l += p; }
;             l += __shfl_xor(l, 32); l += __builtin_amdgcn_exp2f(sink2 - mx);
	v_cndmask_b32_e32 v61, v189, v61, vcc
	v_cndmask_b32_e32 v62, v189, v62, vcc
	v_cndmask_b32_e32 v63, v189, v63, vcc
	v_fmamk_f32 v32, v161, 0x42c00000, v32
	s_cselect_b64 vcc, -1, 0
	v_cndmask_b32_e32 v66, v32, v189, vcc
	v_fmamk_f32 v32, v161, 0x42c20000, v33
	v_cndmask_b32_e32 v67, v32, v189, vcc
	v_fmamk_f32 v32, v161, 0x42c40000, v34
	v_cndmask_b32_e32 v34, v32, v189, vcc
	v_fmamk_f32 v32, v161, 0x42c60000, v35
	v_cndmask_b32_e32 v35, v32, v189, vcc
	v_max3_f32 v16, v16, v14, v15
	v_fmamk_f32 v32, v161, 0x42d00000, v36
	v_max3_f32 v16, v16, v18, v19
	v_cndmask_b32_e32 v36, v32, v189, vcc
	v_max3_f32 v16, v16, v20, v21
	v_fmamk_f32 v32, v161, 0x42d20000, v37
	v_max3_f32 v16, v16, v22, v23
	v_cndmask_b32_e32 v37, v32, v189, vcc
	v_max3_f32 v16, v16, v24, v25
	v_fmamk_f32 v32, v161, 0x42d40000, v38
	v_max3_f32 v16, v16, v26, v27
	v_cndmask_b32_e32 v38, v32, v189, vcc
	v_max3_f32 v16, v16, v28, v29
	v_fmamk_f32 v32, v161, 0x42d60000, v39
	v_max3_f32 v16, v16, v30, v31
	v_cndmask_b32_e32 v39, v32, v189, vcc
	v_max3_f32 v16, v16, v64, v17
	v_fmamk_f32 v32, v161, 0x42e00000, v40
	v_max3_f32 v16, v16, v48, v49
	v_cndmask_b32_e32 v40, v32, v189, vcc
	v_max3_f32 v16, v16, v50, v51
	v_fmamk_f32 v32, v161, 0x42e20000, v41
	v_max3_f32 v16, v16, v52, v53
	v_cndmask_b32_e32 v41, v32, v189, vcc
	v_max3_f32 v16, v16, v54, v55
	v_fmamk_f32 v32, v161, 0x42e40000, v42
	v_max3_f32 v16, v16, v56, v57
	v_cndmask_b32_e32 v42, v32, v189, vcc
	v_max3_f32 v16, v16, v58, v59
	v_fmamk_f32 v32, v161, 0x42e60000, v43
	v_max3_f32 v16, v16, v60, v61
	v_cndmask_b32_e32 v43, v32, v189, vcc
	v_max3_f32 v16, v16, v62, v63
	v_fmamk_f32 v32, v161, 0x42f00000, v44
	v_max3_f32 v16, v16, v66, v67
	v_cndmask_b32_e32 v68, v32, v189, vcc
	v_max3_f32 v16, v16, v34, v35
	v_fmamk_f32 v32, v161, 0x42f20000, v45
	v_max3_f32 v16, v16, v36, v37
	v_cndmask_b32_e32 v69, v32, v189, vcc
	v_max3_f32 v16, v16, v38, v39
	v_fmamk_f32 v32, v161, 0x42f40000, v46
	v_max3_f32 v16, v16, v40, v41
	v_cndmask_b32_e32 v70, v32, v189, vcc
	v_max3_f32 v16, v16, v42, v43
	v_fmamk_f32 v32, v161, 0x42f60000, v47
	v_max3_f32 v16, v16, v68, v69
	v_cndmask_b32_e32 v65, v32, v189, vcc
	v_max3_f32 v16, v16, v70, v65
	v_max3_f32 v16, v16, v219, v220
	v_max3_f32 v16, v16, v217, v216
	v_max3_f32 v16, v16, v214, v213
	v_max3_f32 v16, v16, v215, v212
	v_and_b32_e32 v33, 64, v183
	v_max3_f32 v16, v16, v156, v158
	v_xor_b32_e32 v32, 32, v183
	v_add_u32_e32 v33, 64, v33
	v_max3_f32 v16, v16, v157, v140
	v_cmp_lt_i32_e32 vcc, v32, v33
	v_max3_f32 v16, v16, v136, v133
	v_max3_f32 v16, v16, v134, v132
	v_cndmask_b32_e32 v32, v183, v32, vcc
	v_lshlrev_b32_e32 v32, 2, v32
	ds_bpermute_b32 v33, v32, v16
	v_add_u32_e32 v221, 0x4000, v211
	s_mov_b32 s36, s2
	s_waitcnt lgkmcnt(0)
	v_add_f32_e32 v33, v33, v250
	v_max_f32_e32 v33, v16, v33
	v_sub_f32_e32 v0, v0, v33
	v_exp_f32_e32 v0, v0
	v_sub_f32_e32 v1, v1, v33
	v_exp_f32_e32 v1, v1
	v_sub_f32_e32 v2, v2, v33
	v_exp_f32_e32 v2, v2
	v_sub_f32_e32 v3, v3, v33
	v_exp_f32_e32 v3, v3
	v_sub_f32_e32 v4, v4, v33
	v_add_f32_e32 v16, 0, v0
	v_exp_f32_e32 v4, v4
	v_sub_f32_e32 v5, v5, v33
	v_add_f32_e32 v16, v1, v16
	v_exp_f32_e32 v5, v5
	v_sub_f32_e32 v6, v6, v33
	v_add_f32_e32 v16, v2, v16
	v_exp_f32_e32 v6, v6
	v_sub_f32_e32 v7, v7, v33
	v_add_f32_e32 v16, v3, v16
	v_exp_f32_e32 v7, v7
	v_sub_f32_e32 v8, v8, v33
	v_add_f32_e32 v16, v4, v16
	v_exp_f32_e32 v44, v8
	v_sub_f32_e32 v8, v9, v33
	v_add_f32_e32 v16, v5, v16
	v_exp_f32_e32 v45, v8
	v_sub_f32_e32 v8, v10, v33
	v_add_f32_e32 v16, v6, v16
	v_exp_f32_e32 v46, v8
	v_sub_f32_e32 v9, v11, v33
	v_add_f32_e32 v8, v7, v16
	v_exp_f32_e32 v47, v9
	v_sub_f32_e32 v9, v12, v33
	v_add_f32_e32 v8, v44, v8
	v_exp_f32_e32 v71, v9
	v_sub_f32_e32 v9, v13, v33
	v_add_f32_e32 v8, v45, v8
	v_exp_f32_e32 v72, v9
	v_sub_f32_e32 v9, v14, v33
	v_add_f32_e32 v8, v46, v8
	v_exp_f32_e32 v73, v9
	v_sub_f32_e32 v9, v15, v33
	v_add_f32_e32 v8, v47, v8
	v_exp_f32_e32 v74, v9
	v_sub_f32_e32 v9, v18, v33
	v_add_f32_e32 v8, v71, v8
	v_exp_f32_e32 v75, v9
	v_sub_f32_e32 v9, v19, v33
	v_add_f32_e32 v8, v72, v8
	v_exp_f32_e32 v76, v9
	v_sub_f32_e32 v9, v20, v33
	v_add_f32_e32 v8, v73, v8
	v_exp_f32_e32 v77, v9
	v_sub_f32_e32 v9, v21, v33
	v_add_f32_e32 v8, v74, v8
	v_exp_f32_e32 v78, v9
	v_sub_f32_e32 v9, v22, v33
	v_add_f32_e32 v8, v75, v8
	v_exp_f32_e32 v79, v9
	v_sub_f32_e32 v9, v23, v33
	v_add_f32_e32 v8, v76, v8
	v_exp_f32_e32 v135, v9
	v_sub_f32_e32 v9, v24, v33
	v_add_f32_e32 v8, v77, v8
	v_exp_f32_e32 v137, v9
	v_sub_f32_e32 v9, v25, v33
	v_add_f32_e32 v8, v78, v8
	v_exp_f32_e32 v138, v9
	v_sub_f32_e32 v9, v26, v33
	v_add_f32_e32 v8, v79, v8
	v_exp_f32_e32 v139, v9
	v_sub_f32_e32 v9, v27, v33
	v_add_f32_e32 v8, v135, v8
	v_exp_f32_e32 v141, v9
	v_sub_f32_e32 v9, v28, v33
	v_add_f32_e32 v8, v137, v8
	v_exp_f32_e32 v142, v9
	v_sub_f32_e32 v9, v29, v33
	v_add_f32_e32 v8, v138, v8
	v_exp_f32_e32 v143, v9
	v_sub_f32_e32 v9, v30, v33
	v_add_f32_e32 v8, v139, v8
	v_exp_f32_e32 v144, v9
	v_sub_f32_e32 v9, v31, v33
	v_add_f32_e32 v8, v141, v8
	v_exp_f32_e32 v145, v9
	v_sub_f32_e32 v9, v64, v33
	v_add_f32_e32 v8, v142, v8
	v_exp_f32_e32 v64, v9
	v_sub_f32_e32 v9, v17, v33
	v_add_f32_e32 v8, v143, v8
	v_exp_f32_e32 v146, v9
	v_sub_f32_e32 v9, v48, v33
	v_add_f32_e32 v8, v144, v8
	v_exp_f32_e32 v147, v9
	v_sub_f32_e32 v9, v49, v33
	v_add_f32_e32 v8, v145, v8
	v_exp_f32_e32 v148, v9
	v_sub_f32_e32 v9, v50, v33
	v_add_f32_e32 v8, v64, v8
	v_exp_f32_e32 v50, v9
	v_sub_f32_e32 v9, v51, v33
	v_add_f32_e32 v8, v146, v8
	v_exp_f32_e32 v51, v9
	v_sub_f32_e32 v9, v52, v33
	v_add_f32_e32 v8, v147, v8
	v_exp_f32_e32 v52, v9
	v_sub_f32_e32 v9, v53, v33
	v_add_f32_e32 v8, v148, v8
; __device__ __forceinline__ unsigned cvt_pk_bf16(float lo, float hi) { unsigned r; asm volatile("v_cvt_pk_bf16_f32 %0, %1, %2" : "=v"(r) : "v"(lo), "v"(hi)); return r; }
; #define LAS __attribute__((address_space(3)))
; __device__ __forceinline__ void attn_pool_phase(LAS unsigned char* lds, bf16* QKV, bf16* PL, const float* sinks, int G, int bid) {
;     ...
;             for (int j = 0; j < 5; ++j)
; #pragma unroll
;                 for (int r = 0; r < 16; ++r) { const float p = __builtin_amdgcn_exp2f(S[j][r] - mx); S[j][r] = p; l += p; }
;             l += __shfl_xor(l, 32); l += __builtin_amdgcn_exp2f(sink2 - mx);
;             f32x16 o0 = {}, o1 = {};
; #pragma unroll
;             for (int j = 0; j < 5; ++j)
; #pragma unroll
;                 for (int c = 0; c < 2; ++c) {
;                     u32x4 pw; pw.x = pg8::cvt_pk_bf16(S[j][8 * c + 0], S[j][8 * c + 1]); pw.y = pg8::cvt_pk_bf16(S[j][8 * c + 2], S[j][8 * c + 3]);
;                     pw.z = pg8::cvt_pk_bf16(S[j][8 * c + 4], S[j][8 * c + 5]); pw.w = pg8::cvt_pk_bf16(S[j][8 * c + 6], S[j][8 * c + 7]);
;                     const bf16x8 pb = __builtin_bit_cast(bf16x8, pw);
;                     const LAS unsigned char* vp = lds + LDS_VT + q * VROWB + (32 * (i + j) + 16 * c + 4 * hi) * 2;
;                     const u32x2 a0 = *(const LAS u32x2*)vp, a1 = *(const LAS u32x2*)(vp + 16), b0 = *(const LAS u32x2*)(vp + 32 * VROWB), b1 = *(const LAS u32x2*)(vp + 32 * VROWB + 16);
;                     const bf16x8 va = __builtin_bit_cast(bf16x8, (u32x4){a0.x, a0.y, a1.x, a1.y}), vb = __builtin_bit_cast(bf16x8, (u32x4){b0.x, b0.y, b1.x, b1.y});
;                     o0 = __builtin_amdgcn_mfma_f32_32x32x16_bf16(va, pb, o0, 0, 0, 0);
;                     o1 = __builtin_amdgcn_mfma_f32_32x32x16_bf16(vb, pb, o1, 0, 0, 0); }
	v_exp_f32_e32 v53, v9
	v_sub_f32_e32 v9, v54, v33
	v_add_f32_e32 v8, v50, v8
	v_exp_f32_e32 v54, v9
	v_sub_f32_e32 v9, v55, v33
	v_add_f32_e32 v8, v51, v8
	v_exp_f32_e32 v55, v9
	v_sub_f32_e32 v9, v56, v33
	v_add_f32_e32 v8, v52, v8
	v_exp_f32_e32 v56, v9
	v_sub_f32_e32 v9, v57, v33
	v_add_f32_e32 v8, v53, v8
	v_exp_f32_e32 v57, v9
	v_sub_f32_e32 v9, v58, v33
	v_add_f32_e32 v8, v54, v8
	v_exp_f32_e32 v58, v9
	v_sub_f32_e32 v9, v59, v33
	v_add_f32_e32 v8, v55, v8
	v_exp_f32_e32 v59, v9
	v_sub_f32_e32 v9, v60, v33
	v_add_f32_e32 v8, v56, v8
	v_exp_f32_e32 v60, v9
	v_sub_f32_e32 v9, v61, v33
	v_add_f32_e32 v8, v57, v8
	v_exp_f32_e32 v61, v9
	v_sub_f32_e32 v9, v62, v33
	v_add_f32_e32 v8, v58, v8
	v_exp_f32_e32 v62, v9
	v_sub_f32_e32 v9, v63, v33
	v_add_f32_e32 v8, v59, v8
	v_exp_f32_e32 v63, v9
	v_sub_f32_e32 v9, v66, v33
	v_add_f32_e32 v8, v60, v8
	v_exp_f32_e32 v66, v9
	v_sub_f32_e32 v9, v67, v33
	v_add_f32_e32 v8, v61, v8
	v_exp_f32_e32 v67, v9
	v_sub_f32_e32 v9, v34, v33
	v_add_f32_e32 v8, v62, v8
	v_exp_f32_e32 v149, v9
	v_sub_f32_e32 v9, v35, v33
	v_add_f32_e32 v8, v63, v8
	v_exp_f32_e32 v150, v9
	v_sub_f32_e32 v9, v36, v33
	v_cvt_pk_bf16_f32 v16, v0, v1
	v_cvt_pk_bf16_f32 v17, v2, v3
	v_cvt_pk_bf16_f32 v18, v4, v5
	v_cvt_pk_bf16_f32 v19, v6, v7
	ds_read2_b64 v[0:3], v211 offset1:2
	v_add_f32_e32 v8, v66, v8
	v_exp_f32_e32 v151, v9
	v_sub_f32_e32 v9, v37, v33
	v_add_f32_e32 v8, v67, v8
	v_exp_f32_e32 v152, v9
	v_sub_f32_e32 v9, v38, v33
	v_add_f32_e32 v8, v149, v8
	v_exp_f32_e32 v153, v9
	v_sub_f32_e32 v4, v39, v33
	v_add_f32_e32 v8, v150, v8
	v_exp_f32_e32 v154, v4
	v_sub_f32_e32 v4, v40, v33
	ds_read2_b64 v[20:23], v221 offset0:32 offset1:34
	v_add_f32_e32 v8, v151, v8
	v_exp_f32_e32 v155, v4
	v_sub_f32_e32 v4, v41, v33
	v_add_f32_e32 v8, v152, v8
	v_exp_f32_e32 v159, v4
	v_sub_f32_e32 v24, v42, v33
	v_add_f32_e32 v48, v153, v8
	v_exp_f32_e32 v222, v24
	v_cvt_pk_bf16_f32 v34, v44, v45
	v_cvt_pk_bf16_f32 v35, v46, v47
	v_cvt_pk_bf16_f32 v36, v71, v72
	v_cvt_pk_bf16_f32 v37, v73, v74
	ds_read2_b64 v[38:41], v211 offset0:4 offset1:6
	v_add_f32_e32 v42, v154, v48
	s_waitcnt lgkmcnt(2)
	v_mfma_f32_32x32x16_bf16 v[0:15], v[0:3], v[16:19], 0
	v_add_f32_e32 v42, v155, v42
	v_add_f32_e32 v42, v159, v42
	v_add_f32_e32 v71, v222, v42
	v_sub_f32_e32 v42, v43, v33
	v_exp_f32_e32 v72, v42
	ds_read2_b64 v[42:45], v221 offset0:36 offset1:38
	s_waitcnt lgkmcnt(2)
	v_mfma_f32_32x32x16_bf16 v[16:31], v[20:23], v[16:19], 0
	s_waitcnt lgkmcnt(1)
	v_mfma_f32_32x32x16_bf16 v[0:15], v[38:41], v[34:37], v[0:15]
	v_sub_f32_e32 v38, v68, v33
	v_exp_f32_e32 v68, v38
	v_cvt_pk_bf16_f32 v38, v75, v76
	v_cvt_pk_bf16_f32 v39, v77, v78
	v_cvt_pk_bf16_f32 v40, v79, v135
	v_cvt_pk_bf16_f32 v41, v137, v138
	ds_read2_b64 v[46:49], v211 offset0:8 offset1:10
	s_waitcnt lgkmcnt(1)
	v_mfma_f32_32x32x16_bf16 v[16:31], v[42:45], v[34:37], v[16:31]
	v_add_f32_e32 v34, v72, v71
	v_add_f32_e32 v42, v68, v34
	v_sub_f32_e32 v34, v69, v33
	v_exp_f32_e32 v69, v34
	v_sub_f32_e32 v34, v70, v33
	v_exp_f32_e32 v70, v34
	ds_read2_b64 v[34:37], v221 offset0:40 offset1:42
	v_add_f32_e32 v42, v69, v42
	s_waitcnt lgkmcnt(0)
	v_mfma_f32_32x32x16_bf16 v[16:31], v[34:37], v[38:41], v[16:31]
	v_sub_f32_e32 v34, v65, v33
	v_add_f32_e32 v71, v70, v42
	v_cvt_pk_bf16_f32 v42, v139, v141
	v_cvt_pk_bf16_f32 v43, v142, v143
	v_cvt_pk_bf16_f32 v44, v144, v145
	v_cvt_pk_bf16_f32 v45, v64, v146
	v_exp_f32_e32 v64, v34
	v_sub_f32_e32 v34, v219, v33
	v_exp_f32_e32 v65, v34
	v_sub_f32_e32 v34, v220, v33
	v_exp_f32_e32 v73, v34
	ds_read2_b64 v[34:37], v221 offset0:44 offset1:46
	v_mfma_f32_32x32x16_bf16 v[0:15], v[46:49], v[38:41], v[0:15]
	ds_read2_b64 v[46:49], v211 offset0:12 offset1:14
	v_sub_f32_e32 v38, v217, v33
	v_exp_f32_e32 v74, v38
	v_cvt_pk_bf16_f32 v38, v147, v148
	v_cvt_pk_bf16_f32 v39, v50, v51
	v_cvt_pk_bf16_f32 v40, v52, v53
	v_cvt_pk_bf16_f32 v41, v54, v55
	s_waitcnt lgkmcnt(1)
	v_mfma_f32_32x32x16_bf16 v[16:31], v[34:37], v[42:45], v[16:31]
	v_add_f32_e32 v34, v64, v71
	v_add_f32_e32 v34, v65, v34
	v_add_f32_e32 v34, v73, v34
	v_add_f32_e32 v50, v74, v34
	v_sub_f32_e32 v34, v216, v33
	v_exp_f32_e32 v51, v34
	ds_read2_b64 v[34:37], v221 offset0:48 offset1:50
	s_waitcnt lgkmcnt(1)
	v_mfma_f32_32x32x16_bf16 v[0:15], v[46:49], v[42:45], v[0:15]
	ds_read2_b64 v[46:49], v211 offset0:16 offset1:18
	v_sub_f32_e32 v42, v214, v33
	v_exp_f32_e32 v52, v42
	v_cvt_pk_bf16_f32 v42, v56, v57
	v_cvt_pk_bf16_f32 v43, v58, v59
	v_cvt_pk_bf16_f32 v44, v60, v61
	v_cvt_pk_bf16_f32 v45, v62, v63
	s_waitcnt lgkmcnt(1)
	v_mfma_f32_32x32x16_bf16 v[16:31], v[34:37], v[38:41], v[16:31]
	v_add_f32_e32 v34, v51, v50
	s_waitcnt lgkmcnt(0)
	v_mfma_f32_32x32x16_bf16 v[0:15], v[46:49], v[38:41], v[0:15]
	v_add_f32_e32 v38, v52, v34
	v_sub_f32_e32 v34, v213, v33
	v_exp_f32_e32 v50, v34
	v_sub_f32_e32 v34, v215, v33
	v_exp_f32_e32 v53, v34
	ds_read2_b64 v[34:37], v221 offset0:52 offset1:54
	ds_read2_b64 v[46:49], v211 offset0:20 offset1:22
	s_waitcnt lgkmcnt(1)
	v_mfma_f32_32x32x16_bf16 v[16:31], v[34:37], v[42:45], v[16:31]
	v_sub_f32_e32 v34, v212, v33
	v_exp_f32_e32 v55, v34
	v_sub_f32_e32 v34, v156, v33
	v_add_f32_e32 v38, v50, v38
	v_exp_f32_e32 v56, v34
	v_sub_f32_e32 v34, v158, v33
	v_add_f32_e32 v54, v53, v38
	v_cvt_pk_bf16_f32 v38, v66, v67
	v_cvt_pk_bf16_f32 v39, v149, v150
	v_cvt_pk_bf16_f32 v40, v151, v152
	v_cvt_pk_bf16_f32 v41, v153, v154
	v_exp_f32_e32 v57, v34
	ds_read2_b64 v[34:37], v221 offset0:56 offset1:58
	s_waitcnt lgkmcnt(1)
; #define LAS __attribute__((address_space(3)))
; __device__ __forceinline__ void attn_pool_phase(LAS unsigned char* lds, bf16* QKV, bf16* PL, const float* sinks, int G, int bid) {
;     ...
;                 for (int r = 0; r < 16; ++r) { const float p = __builtin_amdgcn_exp2f(S[j][r] - mx); S[j][r] = p; l += p; }
;             l += __shfl_xor(l, 32); l += __builtin_amdgcn_exp2f(sink2 - mx);
;             f32x16 o0 = {}, o1 = {};
; #pragma unroll
;             for (int j = 0; j < 5; ++j)
; #pragma unroll
;                 for (int c = 0; c < 2; ++c) {
;                     u32x4 pw; pw.x = pg8::cvt_pk_bf16(S[j][8 * c + 0], S[j][8 * c + 1]); pw.y = pg8::cvt_pk_bf16(S[j][8 * c + 2], S[j][8 * c + 3]);
;                     pw.z = pg8::cvt_pk_bf16(S[j][8 * c + 4], S[j][8 * c + 5]); pw.w = pg8::cvt_pk_bf16(S[j][8 * c + 6], S[j][8 * c + 7]);
;                     const bf16x8 pb = __builtin_bit_cast(bf16x8, pw);
;                     const LAS unsigned char* vp = lds + LDS_VT + q * VROWB + (32 * (i + j) + 16 * c + 4 * hi) * 2;
;                     const u32x2 a0 = *(const LAS u32x2*)vp, a1 = *(const LAS u32x2*)(vp + 16), b0 = *(const LAS u32x2*)(vp + 32 * VROWB), b1 = *(const LAS u32x2*)(vp + 32 * VROWB + 16);
;                     const bf16x8 va = __builtin_bit_cast(bf16x8, (u32x4){a0.x, a0.y, a1.x, a1.y}), vb = __builtin_bit_cast(bf16x8, (u32x4){b0.x, b0.y, b1.x, b1.y});
;                     o0 = __builtin_amdgcn_mfma_f32_32x32x16_bf16(va, pb, o0, 0, 0, 0);
;                     o1 = __builtin_amdgcn_mfma_f32_32x32x16_bf16(vb, pb, o1, 0, 0, 0); }
;             const float inv = 1.0f / l;
; #pragma unroll
;             for (int rg = 0; rg < 4; ++rg) { const int d = 8 * rg + 4 * hi;
;                 u32x2 w0, w1; w0.x = pg8::cvt_pk_bf16(o0[4 * rg] * inv, o0[4 * rg + 1] * inv); w0.y = pg8::cvt_pk_bf16(o0[4 * rg + 2] * inv, o0[4 * rg + 3] * inv);
;                 w1.x = pg8::cvt_pk_bf16(o1[4 * rg] * inv, o1[4 * rg + 1] * inv); w1.y = pg8::cvt_pk_bf16(o1[4 * rg + 2] * inv, o1[4 * rg + 3] * inv);
;                 *(LAS u32x2*)(ost + q * OROWB + d * 2) = w0; *(LAS u32x2*)(ost + q * OROWB + (32 + d) * 2) = w1; }
;             asm volatile("s_waitcnt lgkmcnt(0)" ::: "memory");
; #pragma unroll
;             for (int k = 0; k < 4; ++k) { const int r = 8 * k + (lane >> 3), ch = lane & 7;
;                 const u32x4 v = *(const LAS u32x4*)(ost + r * OROWB + ch * 16);
	v_mfma_f32_32x32x16_bf16 v[0:15], v[46:49], v[42:45], v[0:15]
	v_sub_f32_e32 v42, v157, v33
	v_exp_f32_e32 v58, v42
	ds_read2_b64 v[46:49], v211 offset0:24 offset1:26
	v_cvt_pk_bf16_f32 v42, v155, v159
	v_cvt_pk_bf16_f32 v43, v222, v72
	v_cvt_pk_bf16_f32 v44, v68, v69
	v_cvt_pk_bf16_f32 v45, v70, v64
	s_waitcnt lgkmcnt(1)
	v_mfma_f32_32x32x16_bf16 v[16:31], v[34:37], v[38:41], v[16:31]
	v_add_f32_e32 v34, v55, v54
	v_add_f32_e32 v34, v56, v34
	v_add_f32_e32 v34, v57, v34
	v_add_f32_e32 v54, v58, v34
	v_sub_f32_e32 v34, v140, v33
	v_exp_f32_e32 v59, v34
	ds_read2_b64 v[34:37], v221 offset0:60 offset1:62
	s_waitcnt lgkmcnt(1)
	v_mfma_f32_32x32x16_bf16 v[0:15], v[46:49], v[38:41], v[0:15]
	v_sub_f32_e32 v38, v136, v33
	v_exp_f32_e32 v60, v38
	ds_read2_b64 v[46:49], v211 offset0:28 offset1:30
	v_cvt_pk_bf16_f32 v38, v65, v73
	v_cvt_pk_bf16_f32 v39, v74, v51
	v_cvt_pk_bf16_f32 v40, v52, v50
	v_cvt_pk_bf16_f32 v41, v53, v55
	s_waitcnt lgkmcnt(1)
	v_mfma_f32_32x32x16_bf16 v[16:31], v[34:37], v[42:45], v[16:31]
	v_add_f32_e32 v34, v59, v54
	v_add_f32_e32 v50, v60, v34
	v_sub_f32_e32 v34, v133, v33
	v_exp_f32_e32 v51, v34
	v_sub_f32_e32 v34, v134, v33
	v_exp_f32_e32 v52, v34
	ds_read2_b64 v[34:37], v221 offset0:64 offset1:66
	s_waitcnt lgkmcnt(1)
	v_mfma_f32_32x32x16_bf16 v[0:15], v[46:49], v[42:45], v[0:15]
	ds_read2_b64 v[46:49], v211 offset0:32 offset1:34
	v_sub_f32_e32 v42, v132, v33
	v_exp_f32_e32 v53, v42
	v_cvt_pk_bf16_f32 v42, v56, v57
	v_cvt_pk_bf16_f32 v43, v58, v59
	v_cvt_pk_bf16_f32 v44, v60, v51
	v_cvt_pk_bf16_f32 v45, v52, v53
	s_waitcnt lgkmcnt(1)
	v_mfma_f32_32x32x16_bf16 v[16:31], v[34:37], v[38:41], v[16:31]
	v_add_f32_e32 v34, v51, v50
	v_add_f32_e32 v34, v52, v34
	v_add_f32_e32 v36, v53, v34
	ds_bpermute_b32 v37, v32, v36
	v_sub_f32_e32 v32, v249, v33
	s_waitcnt vmcnt(0)
	v_mov_b64_e32 v[134:135], v[118:119]
	v_mov_b64_e32 v[138:139], v[122:123]
	s_waitcnt lgkmcnt(1)
	v_mfma_f32_32x32x16_bf16 v[0:15], v[46:49], v[38:41], v[0:15]
	v_exp_f32_e32 v38, v32
	ds_read2_b64 v[46:49], v211 offset0:36 offset1:38
	ds_read2_b64 v[32:35], v221 offset0:68 offset1:70
	s_waitcnt lgkmcnt(2)
	v_add_f32_e32 v36, v36, v37
	v_add_f32_e32 v36, v38, v36
	v_div_scale_f32 v37, s[8:9], v36, v36, 1.0
	v_rcp_f32_e32 v38, v37
	s_waitcnt lgkmcnt(1)
	v_mfma_f32_32x32x16_bf16 v[0:15], v[46:49], v[42:45], v[0:15]
	v_mov_b64_e32 v[142:143], v[126:127]
	v_add_u32_e32 v211, 64, v211
	v_mov_b64_e32 v[132:133], v[116:117]
	v_mov_b64_e32 v[136:137], v[120:121]
	v_mov_b64_e32 v[140:141], v[124:125]
	s_waitcnt lgkmcnt(0)
	v_mfma_f32_32x32x16_bf16 v[16:31], v[32:35], v[42:45], v[16:31]
	v_fma_f32 v32, -v37, v38, 1.0
	v_fmac_f32_e32 v38, v32, v38
	v_div_scale_f32 v32, vcc, 1.0, v36, 1.0
	v_mul_f32_e32 v33, v32, v38
	v_fma_f32 v34, -v37, v33, v32
	v_fmac_f32_e32 v33, v34, v38
	v_fma_f32 v32, -v37, v33, v32
	v_div_fmas_f32 v32, v32, v38, v33
	v_div_fixup_f32 v32, v32, v36, 1.0
	v_mul_f32_e32 v0, v0, v32
	v_mul_f32_e32 v1, v1, v32
	v_cvt_pk_bf16_f32 v0, v0, v1
	v_mul_f32_e32 v1, v2, v32
	v_mul_f32_e32 v2, v3, v32
	v_cvt_pk_bf16_f32 v1, v1, v2
	v_mul_f32_e32 v2, v16, v32
	v_mul_f32_e32 v3, v17, v32
	v_cvt_pk_bf16_f32 v2, v2, v3
	v_mul_f32_e32 v3, v18, v32
	v_mul_f32_e32 v16, v19, v32
	v_cvt_pk_bf16_f32 v3, v3, v16
	ds_write2_b64 v184, v[0:1], v[2:3] offset1:8
	v_mul_f32_e32 v0, v4, v32
	v_mul_f32_e32 v1, v5, v32
	v_cvt_pk_bf16_f32 v0, v0, v1
	v_mul_f32_e32 v1, v6, v32
	v_mul_f32_e32 v2, v7, v32
	v_cvt_pk_bf16_f32 v1, v1, v2
	v_mul_f32_e32 v2, v20, v32
	v_mul_f32_e32 v3, v21, v32
	v_cvt_pk_bf16_f32 v2, v2, v3
	v_mul_f32_e32 v3, v22, v32
	v_mul_f32_e32 v4, v23, v32
	v_cvt_pk_bf16_f32 v3, v3, v4
	ds_write2_b64 v184, v[0:1], v[2:3] offset0:2 offset1:10
	v_mul_f32_e32 v0, v8, v32
	v_mul_f32_e32 v1, v9, v32
	v_cvt_pk_bf16_f32 v0, v0, v1
	v_mul_f32_e32 v1, v10, v32
	v_mul_f32_e32 v2, v11, v32
	v_cvt_pk_bf16_f32 v1, v1, v2
	v_mul_f32_e32 v2, v24, v32
	v_mul_f32_e32 v3, v25, v32
	v_cvt_pk_bf16_f32 v2, v2, v3
	v_mul_f32_e32 v3, v26, v32
	v_mul_f32_e32 v4, v27, v32
	v_cvt_pk_bf16_f32 v3, v3, v4
	ds_write2_b64 v184, v[0:1], v[2:3] offset0:4 offset1:12
	v_mul_f32_e32 v0, v12, v32
	v_mul_f32_e32 v1, v13, v32
	v_cvt_pk_bf16_f32 v0, v0, v1
	v_mul_f32_e32 v1, v14, v32
	v_mul_f32_e32 v2, v15, v32
	v_cvt_pk_bf16_f32 v1, v1, v2
	v_mul_f32_e32 v2, v28, v32
	v_mul_f32_e32 v3, v29, v32
	v_cvt_pk_bf16_f32 v2, v2, v3
	v_mul_f32_e32 v3, v30, v32
	v_mul_f32_e32 v4, v31, v32
	v_cvt_pk_bf16_f32 v3, v3, v4
	ds_write2_b64 v184, v[0:1], v[2:3] offset0:6 offset1:14
	s_waitcnt lgkmcnt(0)
	ds_read_b128 v[0:3], v185
	ds_read_b128 v[4:7], v185 offset:1152
	v_lshl_add_u64 v[8:9], v[166:167], 0, s[6:7]
	v_add_co_u32_e32 v10, vcc, s39, v8
	s_add_u32 s6, s6, 0x3c000
	s_nop 0
	v_addc_co_u32_e32 v11, vcc, 0, v9, vcc
	s_waitcnt lgkmcnt(1)
	global_store_dwordx4 v[10:11], v[0:3], off sc1
	s_addc_u32 s7, s7, 0
	v_mov_b64_e32 v[32:33], v[128:129]
	v_add_co_u32_e32 v0, vcc, s40, v8
	s_cmp_eq_u32 s6, 0xf0000
	s_nop 0
	v_addc_co_u32_e32 v1, vcc, 0, v9, vcc
	s_waitcnt lgkmcnt(0)
	global_store_dwordx4 v[0:1], v[4:7], off sc1
	ds_read_b128 v[0:3], v185 offset:2304
	ds_read_b128 v[4:7], v185 offset:3456
	v_add_co_u32_e32 v10, vcc, s41, v8
	v_mov_b64_e32 v[34:35], v[130:131]
	s_nop 0
	v_addc_co_u32_e32 v11, vcc, 0, v9, vcc
	s_waitcnt lgkmcnt(1)
	global_store_dwordx4 v[10:11], v[0:3], off sc1
	s_nop 1
	v_add_co_u32_e32 v0, vcc, 0x702d000, v8
	s_nop 1
	v_addc_co_u32_e32 v1, vcc, 0, v9, vcc
	s_waitcnt lgkmcnt(0)
	global_store_dwordx4 v[0:1], v[4:7], off sc1
	s_waitcnt lgkmcnt(0)
	s_cbranch_scc1 .LBB0_494
